# v36 + conversion split at item 8192 (exactly 4 items per wave in P4: 2 loop trips) + first-item gain loads de-serialised in both conversion loops (P1 idle workgroups and P4)
# baseline (speedup 1.0000x reference)
; #define LAS __attribute__((address_space(3)))
; DI void p0_load(const TItem& t, f32x4 (&v)[8], int lane) {
;     const int nblk = t.N / 32, kb = t.item / nblk, nb = t.item % nblk, k0 = 64 * kb, n0 = 32 * nb, c = lane & 7, rr = lane >> 3;
; #pragma unroll
;     for (int i = 0; i < 8; ++i) v[i] = __builtin_nontemporal_load((const f32x4*)(t.W + (size_t)(k0 + 8 * i + rr) * t.N + n0 + 4 * c));
;     if (t.rs) {
; #pragma unroll
;         for (int i = 0; i < 8; ++i) v[i] = v[i] * t.rs[k0 + 8 * i + rr];
;     }
; template <class Resolve>
; DI void p0_convert(const Resolve R, int first, int stride, int total, LAS float* scr, int lane) {
;     for (int it = first; it < total; it += 2 * stride) {
;         const bool two = it + stride < total;
;         const TItem t0 = R(it), t1 = R(two ? it + stride : it);
;         f32x4 v0[8], v1[8];
;         p0_load(t0, v0, lane);
;         if (two) p0_load(t1, v1, lane);
.LBB0_165:
	s_lshr_b32 s7, s19, 5
	v_cvt_f32_u32_e32 v32, s7
	s_sub_i32 s30, 0, s7
	s_abs_i32 s18, s16
	s_ashr_i32 s17, s16, 31
	v_rcp_iflag_f32_e32 v32, v32
	s_nop 0
	v_mul_f32_e32 v32, 0x4f7ffffe, v32
	v_cvt_u32_f32_e32 v32, v32
	s_nop 0
	v_readfirstlane_b32 s31, v32
	s_mul_i32 s30, s30, s31
	s_mul_hi_u32 s30, s31, s30
	s_add_i32 s31, s31, s30
	s_mul_hi_u32 s30, s18, s31
	s_mul_i32 s31, s30, s7
	s_sub_i32 s18, s18, s31
	s_add_i32 s33, s30, 1
	s_sub_i32 s31, s18, s7
	s_cmp_ge_u32 s18, s7
	s_cselect_b32 s30, s33, s30
	s_cselect_b32 s18, s31, s18
	s_add_i32 s31, s30, 1
	s_cmp_ge_u32 s18, s7
	s_cselect_b32 s18, s31, s30
	s_xor_b32 s18, s18, s17
	s_sub_i32 s17, s18, s17
	s_mul_i32 s7, s17, s7
	s_lshl_b32 s18, s17, 6
	s_sub_i32 s7, s16, s7
	v_or_b32_e32 v70, s18, v72
	s_lshl_b32 s16, s7, 5
	v_or_b32_e32 v34, 8, v70
	v_or_b32_e32 v40, 16, v70
	v_or_b32_e32 v42, 24, v70
	v_or_b32_e32 v48, 32, v70
	v_or_b32_e32 v50, 40, v70
	v_or_b32_e32 v56, 48, v70
	v_or_b32_e32 v58, 56, v70
	v_mad_i64_i32 v[32:33], s[30:31], v70, s19, 0
	s_ashr_i32 s17, s16, 31
	v_mad_i64_i32 v[34:35], s[34:35], v34, s19, 0
	v_mad_i64_i32 v[40:41], s[34:35], v40, s19, 0
	v_mad_i64_i32 v[42:43], s[34:35], v42, s19, 0
	v_mad_i64_i32 v[48:49], s[34:35], v48, s19, 0
	v_mad_i64_i32 v[50:51], s[34:35], v50, s19, 0
	v_mad_i64_i32 v[56:57], s[34:35], v56, s19, 0
	v_mad_i64_i32 v[58:59], s[34:35], v58, s19, 0
	v_lshl_add_u64 v[32:33], v[32:33], 2, s[22:23]
	s_lshl_b64 s[30:31], s[16:17], 2
	v_lshl_add_u64 v[34:35], v[34:35], 2, s[22:23]
	v_lshl_add_u64 v[40:41], v[40:41], 2, s[22:23]
	v_lshl_add_u64 v[42:43], v[42:43], 2, s[22:23]
	v_lshl_add_u64 v[48:49], v[48:49], 2, s[22:23]
	v_lshl_add_u64 v[50:51], v[50:51], 2, s[22:23]
	v_lshl_add_u64 v[56:57], v[56:57], 2, s[22:23]
	v_lshl_add_u64 v[58:59], v[58:59], 2, s[22:23]
	v_lshl_add_u64 v[32:33], v[32:33], 0, s[30:31]
	v_lshl_add_u64 v[34:35], v[34:35], 0, s[30:31]
	v_lshl_add_u64 v[40:41], v[40:41], 0, s[30:31]
	v_lshl_add_u64 v[42:43], v[42:43], 0, s[30:31]
	v_lshl_add_u64 v[48:49], v[48:49], 0, s[30:31]
	v_lshl_add_u64 v[50:51], v[50:51], 0, s[30:31]
	v_lshl_add_u64 v[56:57], v[56:57], 0, s[30:31]
	v_lshl_add_u64 v[58:59], v[58:59], 0, s[30:31]
	v_lshl_add_u64 v[32:33], v[32:33], 0, v[68:69]
	v_lshl_add_u64 v[34:35], v[34:35], 0, v[68:69]
	v_lshl_add_u64 v[40:41], v[40:41], 0, v[68:69]
	v_lshl_add_u64 v[42:43], v[42:43], 0, v[68:69]
	v_lshl_add_u64 v[48:49], v[48:49], 0, v[68:69]
	v_lshl_add_u64 v[50:51], v[50:51], 0, v[68:69]
	v_lshl_add_u64 v[56:57], v[56:57], 0, v[68:69]
	v_lshl_add_u64 v[58:59], v[58:59], 0, v[68:69]
	global_load_dwordx4 v[36:39], v[32:33], off nt
	s_nop 0
	global_load_dwordx4 v[32:35], v[34:35], off nt
	s_nop 0
	global_load_dwordx4 v[44:47], v[40:41], off nt
	s_nop 0
	global_load_dwordx4 v[40:43], v[42:43], off nt
	s_nop 0
	global_load_dwordx4 v[52:55], v[48:49], off nt
	s_nop 0
	global_load_dwordx4 v[48:51], v[50:51], off nt
	s_nop 0
	global_load_dwordx4 v[60:63], v[56:57], off nt
	s_nop 0
	global_load_dwordx4 v[56:59], v[58:59], off nt
	s_cmp_eq_u64 s[0:1], 0
	s_cselect_b32 s32, 0, 1
	s_cbranch_scc1 .LBB0_167
	v_ashrrev_i32_e32 v71, 31, v70
	v_lshl_add_u64 v[70:71], v[70:71], 2, s[0:1]
	global_load_dword v92, v[70:71], off
	global_load_dword v94, v[70:71], off offset:32
	global_load_dword v96, v[70:71], off offset:64
	global_load_dword v98, v[70:71], off offset:96
	global_load_dword v100, v[70:71], off offset:128
	global_load_dword v102, v[70:71], off offset:160
	global_load_dword v104, v[70:71], off offset:192
	global_load_dword v106, v[70:71], off offset:224
.LBB0_167:
	v_cndmask_b32_e64 v67, 0, 1, s[20:21]
	v_cmp_ne_u32_e64 s[0:1], 1, v67
	s_andn2_b64 vcc, exec, s[20:21]
	s_cbranch_vccnz .LBB0_170
	s_lshr_b32 s7, s29, 5
	v_cvt_f32_u32_e32 v0, s7
	s_sub_i32 s20, 0, s7
	s_abs_i32 s19, s13
	s_ashr_i32 s17, s13, 31
	v_rcp_iflag_f32_e32 v0, v0
	v_mov_b32_e32 v67, v65
	v_mul_f32_e32 v0, 0x4f7ffffe, v0
	v_cvt_u32_f32_e32 v0, v0
	s_nop 0
	v_readfirstlane_b32 s21, v0
	s_mul_i32 s20, s20, s21
	s_mul_hi_u32 s20, s21, s20
	s_add_i32 s21, s21, s20
	s_mul_hi_u32 s20, s19, s21
	s_mul_i32 s21, s20, s7
	s_sub_i32 s19, s19, s21
	s_add_i32 s22, s20, 1
	s_sub_i32 s21, s19, s7
	s_cmp_ge_u32 s19, s7
	s_cselect_b32 s20, s22, s20
	s_cselect_b32 s19, s21, s19
	s_add_i32 s21, s20, 1
	s_cmp_ge_u32 s19, s7
	s_cselect_b32 s19, s21, s20
	s_xor_b32 s19, s19, s17
	s_sub_i32 s17, s19, s17
	s_mul_i32 s7, s17, s7
	v_lshl_or_b32 v70, s17, 6, v72
	s_sub_i32 s7, s13, s7
	v_mad_i64_i32 v[0:1], s[20:21], v70, s29, 0
	s_lshl_b32 s20, s7, 5
	v_or_b32_e32 v2, 8, v70
	v_or_b32_e32 v8, 16, v70
	v_or_b32_e32 v10, 24, v70
	v_or_b32_e32 v16, 32, v70
	v_or_b32_e32 v18, 40, v70
	v_or_b32_e32 v24, 48, v70
	v_or_b32_e32 v26, 56, v70
	s_ashr_i32 s21, s20, 31
	v_mad_i64_i32 v[2:3], s[22:23], v2, s29, 0
	v_mad_i64_i32 v[8:9], s[22:23], v8, s29, 0
	v_mad_i64_i32 v[10:11], s[22:23], v10, s29, 0
	v_mad_i64_i32 v[16:17], s[22:23], v16, s29, 0
	v_mad_i64_i32 v[18:19], s[22:23], v18, s29, 0
	v_mad_i64_i32 v[24:25], s[22:23], v24, s29, 0
	v_mad_i64_i32 v[26:27], s[22:23], v26, s29, 0
	v_lshl_add_u64 v[0:1], v[0:1], 2, s[4:5]
	s_lshl_b64 s[20:21], s[20:21], 2
	v_lshl_add_u64 v[2:3], v[2:3], 2, s[4:5]
	v_lshl_add_u64 v[8:9], v[8:9], 2, s[4:5]
	v_lshl_add_u64 v[10:11], v[10:11], 2, s[4:5]
	v_lshl_add_u64 v[16:17], v[16:17], 2, s[4:5]
	v_lshl_add_u64 v[18:19], v[18:19], 2, s[4:5]
	v_lshl_add_u64 v[24:25], v[24:25], 2, s[4:5]
	v_lshl_add_u64 v[26:27], v[26:27], 2, s[4:5]
	v_lshl_add_u64 v[0:1], v[0:1], 0, s[20:21]
	v_lshl_add_u64 v[2:3], v[2:3], 0, s[20:21]
	v_lshl_add_u64 v[8:9], v[8:9], 0, s[20:21]
	v_lshl_add_u64 v[10:11], v[10:11], 0, s[20:21]
	v_lshl_add_u64 v[16:17], v[16:17], 0, s[20:21]
	v_lshl_add_u64 v[18:19], v[18:19], 0, s[20:21]
	v_lshl_add_u64 v[24:25], v[24:25], 0, s[20:21]
	v_lshl_add_u64 v[26:27], v[26:27], 0, s[20:21]
	v_lshl_add_u64 v[0:1], v[0:1], 0, v[66:67]
	v_lshl_add_u64 v[4:5], v[2:3], 0, v[66:67]
	v_lshl_add_u64 v[8:9], v[8:9], 0, v[66:67]
	v_lshl_add_u64 v[12:13], v[10:11], 0, v[66:67]
	v_lshl_add_u64 v[16:17], v[16:17], 0, v[66:67]
	v_lshl_add_u64 v[20:21], v[18:19], 0, v[66:67]
	v_lshl_add_u64 v[24:25], v[24:25], 0, v[66:67]
	v_lshl_add_u64 v[28:29], v[26:27], 0, v[66:67]
	global_load_dwordx4 v[0:3], v[0:1], off nt
	s_nop 0
	global_load_dwordx4 v[4:7], v[4:5], off nt
	s_nop 0
	global_load_dwordx4 v[8:11], v[8:9], off nt
	s_nop 0
	global_load_dwordx4 v[12:15], v[12:13], off nt
	s_nop 0
	global_load_dwordx4 v[16:19], v[16:17], off nt
	s_nop 0
	global_load_dwordx4 v[20:23], v[20:21], off nt
	s_nop 0
	global_load_dwordx4 v[24:27], v[24:25], off nt
	s_nop 0
	global_load_dwordx4 v[28:31], v[28:29], off nt
	s_cmp_eq_u64 s[2:3], 0
	s_cbranch_scc1 .LBB0_170
; #define LAS __attribute__((address_space(3)))
; DI unsigned pk2(float lo, float hi) { f32x2 v = {lo, hi}; return __builtin_bit_cast(unsigned, __builtin_convertvector(v, bf16x2v)); }
; DI void p0_load(const TItem& t, f32x4 (&v)[8], int lane) {
;     ...
;     if (t.rs) {
; #pragma unroll
;         for (int i = 0; i < 8; ++i) v[i] = v[i] * t.rs[k0 + 8 * i + rr];
;     }
; }
; DI void p0_store(const TItem& t, const f32x4 (&v)[8], LAS float* scr, int lane) {
;     const int nblk = t.N / 32, kb = t.item / nblk, nb = t.item % nblk, k0 = 64 * kb, n0 = 32 * nb, c = lane & 7, rr = lane >> 3;
; #pragma unroll
;     for (int i = 0; i < 8; ++i) { LAS float* d = scr + (8 * i + rr) * 33 + 4 * c; d[0] = v[i][0]; d[1] = v[i][1]; d[2] = v[i][2]; d[3] = v[i][3]; }
;     asm volatile("s_waitcnt lgkmcnt(0)" ::: "memory");
; #pragma unroll
;     for (int j = 0; j < 4; ++j) { const int n = (lane >> 3) + 8 * j; const LAS float* s = scr + (8 * c) * 33 + n;
;         u32x4 o; o.x = pk2(s[0 * 33], s[1 * 33]); o.y = pk2(s[2 * 33], s[3 * 33]); o.z = pk2(s[4 * 33], s[5 * 33]); o.w = pk2(s[6 * 33], s[7 * 33]);
;         *(u32x4*)(t.WT + (size_t)(n0 + n) * t.K + k0 + 8 * c) = o; }
;     asm volatile("s_waitcnt lgkmcnt(0)" ::: "memory");
; }
; template <class Resolve>
; DI void p0_convert(const Resolve R, int first, int stride, int total, LAS float* scr, int lane) {
;     for (int it = first; it < total; it += 2 * stride) {
;         const bool two = it + stride < total;
;         const TItem t0 = R(it), t1 = R(two ? it + stride : it);
;         f32x4 v0[8], v1[8];
;         p0_load(t0, v0, lane);
;         if (two) p0_load(t1, v1, lane);
;         p0_store(t0, v0, scr, lane);
;         if (two) p0_store(t1, v1, scr + 64 * 33, lane);
;     }
	v_ashrrev_i32_e32 v71, 31, v70
	v_lshl_add_u64 v[70:71], v[70:71], 2, s[2:3]
	global_load_dword v78, v[70:71], off
	global_load_dword v80, v[70:71], off offset:32
	global_load_dword v82, v[70:71], off offset:64
	global_load_dword v84, v[70:71], off offset:96
	global_load_dword v86, v[70:71], off offset:128
	global_load_dword v88, v[70:71], off offset:160
	global_load_dword v90, v[70:71], off offset:192
	s_nop 0
	global_load_dword v70, v[70:71], off offset:224
	s_waitcnt vmcnt(0)
	v_pk_mul_f32 v[2:3], v[2:3], v[78:79] op_sel_hi:[1,0]
	v_pk_mul_f32 v[0:1], v[0:1], v[78:79] op_sel_hi:[1,0]
	v_pk_mul_f32 v[6:7], v[6:7], v[80:81] op_sel_hi:[1,0]
	v_pk_mul_f32 v[4:5], v[4:5], v[80:81] op_sel_hi:[1,0]
	v_pk_mul_f32 v[10:11], v[10:11], v[82:83] op_sel_hi:[1,0]
	v_pk_mul_f32 v[8:9], v[8:9], v[82:83] op_sel_hi:[1,0]
	v_pk_mul_f32 v[14:15], v[14:15], v[84:85] op_sel_hi:[1,0]
	v_pk_mul_f32 v[12:13], v[12:13], v[84:85] op_sel_hi:[1,0]
	v_pk_mul_f32 v[18:19], v[18:19], v[86:87] op_sel_hi:[1,0]
	v_pk_mul_f32 v[16:17], v[16:17], v[86:87] op_sel_hi:[1,0]
	v_pk_mul_f32 v[22:23], v[22:23], v[88:89] op_sel_hi:[1,0]
	v_pk_mul_f32 v[20:21], v[20:21], v[88:89] op_sel_hi:[1,0]
	v_pk_mul_f32 v[26:27], v[26:27], v[90:91] op_sel_hi:[1,0]
	v_pk_mul_f32 v[24:25], v[24:25], v[90:91] op_sel_hi:[1,0]
	v_pk_mul_f32 v[30:31], v[30:31], v[70:71] op_sel_hi:[1,0]
	v_pk_mul_f32 v[28:29], v[28:29], v[70:71] op_sel_hi:[1,0]
.LBB0_170:
	s_waitcnt vmcnt(0)
	s_cmp_eq_u32 s32, 0
	s_cbranch_scc1 .Lmy_g0skip_p1
	v_pk_mul_f32 v[38:39], v[38:39], v[92:93] op_sel_hi:[1,0]
	v_pk_mul_f32 v[36:37], v[36:37], v[92:93] op_sel_hi:[1,0]
	v_pk_mul_f32 v[34:35], v[34:35], v[94:95] op_sel_hi:[1,0]
	v_pk_mul_f32 v[32:33], v[32:33], v[94:95] op_sel_hi:[1,0]
	v_pk_mul_f32 v[46:47], v[46:47], v[96:97] op_sel_hi:[1,0]
	v_pk_mul_f32 v[44:45], v[44:45], v[96:97] op_sel_hi:[1,0]
	v_pk_mul_f32 v[42:43], v[42:43], v[98:99] op_sel_hi:[1,0]
	v_pk_mul_f32 v[40:41], v[40:41], v[98:99] op_sel_hi:[1,0]
	v_pk_mul_f32 v[54:55], v[54:55], v[100:101] op_sel_hi:[1,0]
	v_pk_mul_f32 v[52:53], v[52:53], v[100:101] op_sel_hi:[1,0]
	v_pk_mul_f32 v[50:51], v[50:51], v[102:103] op_sel_hi:[1,0]
	v_pk_mul_f32 v[48:49], v[48:49], v[102:103] op_sel_hi:[1,0]
	v_pk_mul_f32 v[62:63], v[62:63], v[104:105] op_sel_hi:[1,0]
	v_pk_mul_f32 v[60:61], v[60:61], v[104:105] op_sel_hi:[1,0]
	v_pk_mul_f32 v[58:59], v[58:59], v[106:107] op_sel_hi:[1,0]
	v_pk_mul_f32 v[56:57], v[56:57], v[106:107] op_sel_hi:[1,0]
.Lmy_g0skip_p1:
	ds_write2_b32 v77, v36, v37 offset1:1
	ds_write2_b32 v77, v38, v39 offset0:2 offset1:3
	v_add_u32_e32 v36, 0x420, v77
	ds_write2_b32 v36, v32, v33 offset1:1
	v_add_u32_e32 v32, 0x428, v77
	ds_write2_b32 v32, v34, v35 offset1:1
	v_add_u32_e32 v32, 0x840, v77
	ds_write2_b32 v32, v44, v45 offset1:1
	v_add_u32_e32 v32, 0x848, v77
	ds_write2_b32 v32, v46, v47 offset1:1
	v_add_u32_e32 v32, 0xc60, v77
	ds_write2_b32 v32, v40, v41 offset1:1
	v_add_u32_e32 v32, 0xc68, v77
	ds_write2_b32 v32, v42, v43 offset1:1
	v_add_u32_e32 v32, 0x1080, v77
	ds_write2_b32 v32, v52, v53 offset1:1
	v_add_u32_e32 v32, 0x1088, v77
	ds_write2_b32 v32, v54, v55 offset1:1
	v_add_u32_e32 v32, 0x14a0, v77
	ds_write2_b32 v32, v48, v49 offset1:1
	v_add_u32_e32 v32, 0x14a8, v77
	ds_write2_b32 v32, v50, v51 offset1:1
	v_add_u32_e32 v32, 0x18c0, v77
	ds_write2_b32 v32, v60, v61 offset1:1
	v_add_u32_e32 v32, 0x18c8, v77
	ds_write2_b32 v32, v62, v63 offset1:1
	v_add_u32_e32 v32, 0x1ce0, v77
	ds_write2_b32 v32, v56, v57 offset1:1
	v_add_u32_e32 v32, 0x1ce8, v77
	ds_write2_b32 v32, v58, v59 offset1:1
	s_waitcnt lgkmcnt(0)
	ds_read2_b32 v[36:37], v76 offset0:33 offset1:41
	ds_read2_b32 v[38:39], v76 offset1:8
	ds_read2_b32 v[40:41], v76 offset0:66 offset1:74
	ds_read2_b32 v[42:43], v76 offset0:99 offset1:107
	ds_read2_b32 v[44:45], v76 offset0:132 offset1:140
	ds_read2_b32 v[46:47], v76 offset0:165 offset1:173
	ds_read2_b32 v[48:49], v76 offset0:198 offset1:206
	ds_read2_b32 v[50:51], v76 offset0:231 offset1:239
	s_waitcnt lgkmcnt(6)
	v_cvt_pk_bf16_f32 v32, v38, v36
	v_or_b32_e32 v36, s16, v72
	s_ashr_i32 s19, s18, 31
	v_mad_i64_i32 v[52:53], s[2:3], s12, v36, 0
	v_lshl_add_u64 v[52:53], v[52:53], 1, s[14:15]
	s_lshl_b64 s[2:3], s[18:19], 1
	v_lshl_add_u64 v[52:53], v[52:53], 0, s[2:3]
	s_waitcnt lgkmcnt(4)
	v_cvt_pk_bf16_f32 v33, v40, v42
	s_waitcnt lgkmcnt(2)
	v_cvt_pk_bf16_f32 v34, v44, v46
	s_waitcnt lgkmcnt(0)
	v_cvt_pk_bf16_f32 v35, v48, v50
	v_lshl_add_u64 v[52:53], v[52:53], 0, v[64:65]
	v_or_b32_e32 v36, s16, v73
	global_store_dwordx4 v[52:53], v[32:35], off
	s_and_b64 vcc, exec, s[0:1]
	s_nop 0
	v_cvt_pk_bf16_f32 v32, v39, v37
	v_mad_i64_i32 v[36:37], s[4:5], s12, v36, 0
	v_lshl_add_u64 v[36:37], v[36:37], 1, s[14:15]
	v_lshl_add_u64 v[36:37], v[36:37], 0, s[2:3]
	v_cvt_pk_bf16_f32 v33, v41, v43
	v_cvt_pk_bf16_f32 v34, v45, v47
	v_cvt_pk_bf16_f32 v35, v49, v51
	v_lshl_add_u64 v[36:37], v[36:37], 0, v[64:65]
	ds_read2_b32 v[38:39], v76 offset0:16 offset1:24
	ds_read2_b32 v[40:41], v76 offset0:49 offset1:57
	ds_read2_b32 v[42:43], v76 offset0:82 offset1:90
	ds_read2_b32 v[44:45], v76 offset0:115 offset1:123
	ds_read2_b32 v[46:47], v76 offset0:148 offset1:156
	ds_read2_b32 v[48:49], v76 offset0:181 offset1:189
	ds_read2_b32 v[50:51], v76 offset0:214 offset1:222
	ds_read2_b32 v[52:53], v76 offset0:247 offset1:255
	global_store_dwordx4 v[36:37], v[32:35], off
	v_or_b32_e32 v36, s16, v74
	v_mad_i64_i32 v[36:37], s[4:5], s12, v36, 0
	v_lshl_add_u64 v[36:37], v[36:37], 1, s[14:15]
	v_lshl_add_u64 v[36:37], v[36:37], 0, s[2:3]
	s_waitcnt lgkmcnt(6)
	v_cvt_pk_bf16_f32 v32, v38, v40
	s_waitcnt lgkmcnt(4)
	v_cvt_pk_bf16_f32 v33, v42, v44
	s_waitcnt lgkmcnt(2)
	v_cvt_pk_bf16_f32 v34, v46, v48
	s_waitcnt lgkmcnt(0)
	v_cvt_pk_bf16_f32 v35, v50, v52
	v_lshl_add_u64 v[36:37], v[36:37], 0, v[64:65]
	global_store_dwordx4 v[36:37], v[32:35], off
	v_or_b32_e32 v36, s16, v75
	v_mad_i64_i32 v[36:37], s[4:5], s12, v36, 0
	v_lshl_add_u64 v[36:37], v[36:37], 1, s[14:15]
	v_lshl_add_u64 v[36:37], v[36:37], 0, s[2:3]
	v_cvt_pk_bf16_f32 v32, v39, v41
	v_cvt_pk_bf16_f32 v33, v43, v45
	v_cvt_pk_bf16_f32 v34, v47, v49
	v_cvt_pk_bf16_f32 v35, v51, v53
	v_lshl_add_u64 v[36:37], v[36:37], 0, v[64:65]
	global_store_dwordx4 v[36:37], v[32:35], off
	s_waitcnt lgkmcnt(0)
	s_cbranch_vccnz .LBB0_150
; #define LAS __attribute__((address_space(3)))
; DI unsigned pk2(float lo, float hi) { f32x2 v = {lo, hi}; return __builtin_bit_cast(unsigned, __builtin_convertvector(v, bf16x2v)); }
; DI void p0_store(const TItem& t, const f32x4 (&v)[8], LAS float* scr, int lane) {
;     const int nblk = t.N / 32, kb = t.item / nblk, nb = t.item % nblk, k0 = 64 * kb, n0 = 32 * nb, c = lane & 7, rr = lane >> 3;
; #pragma unroll
;     for (int i = 0; i < 8; ++i) { LAS float* d = scr + (8 * i + rr) * 33 + 4 * c; d[0] = v[i][0]; d[1] = v[i][1]; d[2] = v[i][2]; d[3] = v[i][3]; }
;     asm volatile("s_waitcnt lgkmcnt(0)" ::: "memory");
; #pragma unroll
;     for (int j = 0; j < 4; ++j) { const int n = (lane >> 3) + 8 * j; const LAS float* s = scr + (8 * c) * 33 + n;
;         u32x4 o; o.x = pk2(s[0 * 33], s[1 * 33]); o.y = pk2(s[2 * 33], s[3 * 33]); o.z = pk2(s[4 * 33], s[5 * 33]); o.w = pk2(s[6 * 33], s[7 * 33]);
;         *(u32x4*)(t.WT + (size_t)(n0 + n) * t.K + k0 + 8 * c) = o; }
;     asm volatile("s_waitcnt lgkmcnt(0)" ::: "memory");
; }
; template <class Resolve>
; DI void p0_convert(const Resolve R, int first, int stride, int total, LAS float* scr, int lane) {
;     for (int it = first; it < total; it += 2 * stride) {
;         const bool two = it + stride < total;
;         const TItem t0 = R(it), t1 = R(two ? it + stride : it);
;         f32x4 v0[8], v1[8];
;         p0_load(t0, v0, lane);
;         if (two) p0_load(t1, v1, lane);
;         p0_store(t0, v0, scr, lane);
;         if (two) p0_store(t1, v1, scr + 64 * 33, lane);
;     }
	s_lshr_b32 s1, s29, 5
	v_cvt_f32_u32_e32 v32, s1
	s_sub_i32 s3, 0, s1
	v_add_u32_e32 v33, 0x2100, v77
	v_add_u32_e32 v34, 0x2108, v77
	v_rcp_iflag_f32_e32 v32, v32
	ds_write2_b32 v33, v0, v1 offset1:1
	ds_write2_b32 v34, v2, v3 offset1:1
	s_abs_i32 s2, s13
	s_ashr_i32 s0, s13, 31
	v_mul_f32_e32 v32, 0x4f7ffffe, v32
	v_cvt_u32_f32_e32 v32, v32
	v_add_u32_e32 v54, 0x2000, v76
	v_add_u32_e32 v55, 0x2400, v76
	v_readfirstlane_b32 s4, v32
	s_mul_i32 s3, s3, s4
	v_add_u32_e32 v32, 0x2520, v77
	s_mul_hi_u32 s3, s4, s3
	ds_write2_b32 v32, v4, v5 offset1:1
	v_add_u32_e32 v32, 0x2528, v77
	s_add_i32 s4, s4, s3
	ds_write2_b32 v32, v6, v7 offset1:1
	v_add_u32_e32 v32, 0x2940, v77
	s_mul_hi_u32 s3, s2, s4
	ds_write2_b32 v32, v8, v9 offset1:1
	v_add_u32_e32 v32, 0x2948, v77
	s_mul_i32 s4, s3, s1
	ds_write2_b32 v32, v10, v11 offset1:1
	v_add_u32_e32 v32, 0x2d60, v77
	s_sub_i32 s2, s2, s4
	ds_write2_b32 v32, v12, v13 offset1:1
	v_add_u32_e32 v32, 0x2d68, v77
	s_add_i32 s5, s3, 1
	s_sub_i32 s4, s2, s1
	ds_write2_b32 v32, v14, v15 offset1:1
	v_add_u32_e32 v32, 0x3180, v77
	s_cmp_ge_u32 s2, s1
	ds_write2_b32 v32, v16, v17 offset1:1
	v_add_u32_e32 v32, 0x3188, v77
	s_cselect_b32 s3, s5, s3
	ds_write2_b32 v32, v18, v19 offset1:1
	v_add_u32_e32 v32, 0x35a0, v77
	s_cselect_b32 s2, s4, s2
	s_add_i32 s4, s3, 1
	ds_write2_b32 v32, v20, v21 offset1:1
	v_add_u32_e32 v32, 0x35a8, v77
	s_cmp_ge_u32 s2, s1
	ds_write2_b32 v32, v22, v23 offset1:1
	v_add_u32_e32 v32, 0x39c0, v77
	s_cselect_b32 s2, s4, s3
	ds_write2_b32 v32, v24, v25 offset1:1
	v_add_u32_e32 v32, 0x39c8, v77
	s_xor_b32 s2, s2, s0
	ds_write2_b32 v32, v26, v27 offset1:1
	v_add_u32_e32 v32, 0x3de0, v77
	s_sub_i32 s2, s2, s0
	ds_write2_b32 v32, v28, v29 offset1:1
	v_add_u32_e32 v32, 0x3de8, v77
	s_lshl_b32 s0, s2, 6
	ds_write2_b32 v32, v30, v31 offset1:1
	s_mul_i32 s2, s2, s1
	s_sub_i32 s1, s13, s2
	s_waitcnt lgkmcnt(0)
	s_lshl_b32 s4, s1, 5
	ds_read2_b32 v[36:37], v54 offset0:97 offset1:105
	ds_read2_b32 v[38:39], v54 offset0:64 offset1:72
	ds_read2_b32 v[40:41], v54 offset0:130 offset1:138
	ds_read2_b32 v[42:43], v54 offset0:163 offset1:171
	ds_read2_b32 v[44:45], v54 offset0:196 offset1:204
	ds_read2_b32 v[46:47], v54 offset0:229 offset1:237
	ds_read2_b32 v[48:49], v55 offset0:6 offset1:14
	ds_read2_b32 v[50:51], v55 offset0:39 offset1:47
	s_waitcnt lgkmcnt(6)
	v_cvt_pk_bf16_f32 v32, v38, v36
	v_or_b32_e32 v36, s4, v72
	s_ashr_i32 s1, s0, 31
	v_mad_i64_i32 v[52:53], s[2:3], s6, v36, 0
	v_lshl_add_u64 v[52:53], v[52:53], 1, s[8:9]
	s_lshl_b64 s[0:1], s[0:1], 1
	v_lshl_add_u64 v[52:53], v[52:53], 0, s[0:1]
	s_waitcnt lgkmcnt(4)
	v_cvt_pk_bf16_f32 v33, v40, v42
	s_waitcnt lgkmcnt(2)
	v_cvt_pk_bf16_f32 v34, v44, v46
	s_waitcnt lgkmcnt(0)
	v_cvt_pk_bf16_f32 v35, v48, v50
	v_lshl_add_u64 v[52:53], v[52:53], 0, v[64:65]
	v_or_b32_e32 v36, s4, v73
	global_store_dwordx4 v[52:53], v[32:35], off
	s_nop 1
	v_cvt_pk_bf16_f32 v32, v39, v37
	v_mad_i64_i32 v[36:37], s[2:3], s6, v36, 0
	v_lshl_add_u64 v[36:37], v[36:37], 1, s[8:9]
	v_lshl_add_u64 v[36:37], v[36:37], 0, s[0:1]
	v_cvt_pk_bf16_f32 v33, v41, v43
	v_cvt_pk_bf16_f32 v34, v45, v47
	v_cvt_pk_bf16_f32 v35, v49, v51
	v_lshl_add_u64 v[36:37], v[36:37], 0, v[64:65]
	ds_read2_b32 v[38:39], v54 offset0:80 offset1:88
	ds_read2_b32 v[40:41], v54 offset0:113 offset1:121
	ds_read2_b32 v[42:43], v54 offset0:146 offset1:154
	ds_read2_b32 v[44:45], v54 offset0:179 offset1:187
	ds_read2_b32 v[46:47], v54 offset0:212 offset1:220
	ds_read2_b32 v[48:49], v54 offset0:245 offset1:253
	ds_read2_b32 v[50:51], v55 offset0:22 offset1:30
	ds_read2_b32 v[52:53], v55 offset0:55 offset1:63
	global_store_dwordx4 v[36:37], v[32:35], off
	v_or_b32_e32 v36, s4, v74
	v_mad_i64_i32 v[36:37], s[2:3], s6, v36, 0
	v_lshl_add_u64 v[36:37], v[36:37], 1, s[8:9]
	v_lshl_add_u64 v[36:37], v[36:37], 0, s[0:1]
	s_waitcnt lgkmcnt(6)
	v_cvt_pk_bf16_f32 v32, v38, v40
	s_waitcnt lgkmcnt(4)
	v_cvt_pk_bf16_f32 v33, v42, v44
	s_waitcnt lgkmcnt(2)
	v_cvt_pk_bf16_f32 v34, v46, v48
	s_waitcnt lgkmcnt(0)
	v_cvt_pk_bf16_f32 v35, v50, v52
	v_lshl_add_u64 v[36:37], v[36:37], 0, v[64:65]
	global_store_dwordx4 v[36:37], v[32:35], off
	v_or_b32_e32 v36, s4, v75
	v_mad_i64_i32 v[36:37], s[2:3], s6, v36, 0
	v_lshl_add_u64 v[36:37], v[36:37], 1, s[8:9]
	v_lshl_add_u64 v[36:37], v[36:37], 0, s[0:1]
	v_cvt_pk_bf16_f32 v32, v39, v41
	v_cvt_pk_bf16_f32 v33, v43, v45
	v_cvt_pk_bf16_f32 v34, v47, v49
	v_cvt_pk_bf16_f32 v35, v51, v53
	v_lshl_add_u64 v[36:37], v[36:37], 0, v[64:65]
	global_store_dwordx4 v[36:37], v[32:35], off
	s_waitcnt lgkmcnt(0)
	s_branch .LBB0_150
